# s5_chunk inter-chunk scan: 8-step unrolled batches, LDS operands read ahead, scalar f32 ops in the same order, incremental store addresses
# baseline (speedup 1.0000x reference)
.LBB0_699:
	v_lshlrev_b32_e32 v85, s91, v76
	s_waitcnt vmcnt(0)
	s_add_i32 s25, s90, 1
	s_lshr_b32 s25, s25, 3
	s_and_b64 s[4:5], s[42:43], exec
	s_cbranch_scc0 .Lsc_d1
	v_add_u32_e32 v210, s92, v85
	v_mov_b32_e32 v211, 0
	v_lshlrev_b32_e32 v210, 15, v210
	v_lshl_add_u64 v[208:209], v[210:211], 0, v[66:67]
	v_lshl_add_u32 v212, v85, 9, v84
	s_mov_b64 s[4:5], 0x8000
.Lsc_b0:
	s_waitcnt vmcnt(40)
	ds_read2st64_b32 v[176:177], v212 offset0:0 offset1:1
	ds_read2st64_b32 v[178:179], v212 offset0:2 offset1:3
	ds_read2st64_b32 v[180:181], v212 offset0:4 offset1:5
	ds_read2st64_b32 v[182:183], v212 offset0:6 offset1:7
	ds_read2st64_b32 v[184:185], v212 offset0:8 offset1:9
	ds_read2st64_b32 v[186:187], v212 offset0:10 offset1:11
	ds_read2st64_b32 v[188:189], v212 offset0:12 offset1:13
	ds_read2st64_b32 v[190:191], v212 offset0:14 offset1:15
	v_cvt_pk_bf16_f32 v213, v75, s0
	v_cvt_pk_bf16_f32 v214, v74, s0
	global_store_short v[208:209], v213, off
	global_store_short v[208:209], v214, off offset:128
	v_mul_f32_e32 v217, v70, v74
	v_mul_f32_e32 v218, v71, v74
	v_fma_f32 v219, v71, v75, v217
	v_fma_f32 v220, v70, v75, -v218
	s_waitcnt lgkmcnt(7)
	v_add_f32_e32 v74, v219, v177
	v_add_f32_e32 v75, v220, v176
	v_lshl_add_u64 v[208:209], v[208:209], 0, s[4:5]
	v_cvt_pk_bf16_f32 v215, v75, s0
	v_cvt_pk_bf16_f32 v216, v74, s0
	global_store_short v[208:209], v215, off
	global_store_short v[208:209], v216, off offset:128
	v_mul_f32_e32 v217, v70, v74
	v_mul_f32_e32 v218, v71, v74
	v_fma_f32 v219, v71, v75, v217
	v_fma_f32 v220, v70, v75, -v218
	s_waitcnt lgkmcnt(6)
	v_add_f32_e32 v74, v219, v179
	v_add_f32_e32 v75, v220, v178
	v_lshl_add_u64 v[208:209], v[208:209], 0, s[4:5]
	v_cvt_pk_bf16_f32 v213, v75, s0
	v_cvt_pk_bf16_f32 v214, v74, s0
	global_store_short v[208:209], v213, off
	global_store_short v[208:209], v214, off offset:128
	v_mul_f32_e32 v217, v70, v74
	v_mul_f32_e32 v218, v71, v74
	v_fma_f32 v219, v71, v75, v217
	v_fma_f32 v220, v70, v75, -v218
	s_waitcnt lgkmcnt(5)
	v_add_f32_e32 v74, v219, v181
	v_add_f32_e32 v75, v220, v180
	v_lshl_add_u64 v[208:209], v[208:209], 0, s[4:5]
	v_cvt_pk_bf16_f32 v215, v75, s0
	v_cvt_pk_bf16_f32 v216, v74, s0
	global_store_short v[208:209], v215, off
	global_store_short v[208:209], v216, off offset:128
	v_mul_f32_e32 v217, v70, v74
	v_mul_f32_e32 v218, v71, v74
	v_fma_f32 v219, v71, v75, v217
	v_fma_f32 v220, v70, v75, -v218
	s_waitcnt lgkmcnt(4)
	v_add_f32_e32 v74, v219, v183
	v_add_f32_e32 v75, v220, v182
	v_lshl_add_u64 v[208:209], v[208:209], 0, s[4:5]
	v_cvt_pk_bf16_f32 v213, v75, s0
	v_cvt_pk_bf16_f32 v214, v74, s0
	global_store_short v[208:209], v213, off
	global_store_short v[208:209], v214, off offset:128
	v_mul_f32_e32 v217, v70, v74
	v_mul_f32_e32 v218, v71, v74
	v_fma_f32 v219, v71, v75, v217
	v_fma_f32 v220, v70, v75, -v218
	s_waitcnt lgkmcnt(3)
	v_add_f32_e32 v74, v219, v185
	v_add_f32_e32 v75, v220, v184
	v_lshl_add_u64 v[208:209], v[208:209], 0, s[4:5]
	v_cvt_pk_bf16_f32 v215, v75, s0
	v_cvt_pk_bf16_f32 v216, v74, s0
	global_store_short v[208:209], v215, off
	global_store_short v[208:209], v216, off offset:128
	v_mul_f32_e32 v217, v70, v74
	v_mul_f32_e32 v218, v71, v74
	v_fma_f32 v219, v71, v75, v217
	v_fma_f32 v220, v70, v75, -v218
	s_waitcnt lgkmcnt(2)
	v_add_f32_e32 v74, v219, v187
	v_add_f32_e32 v75, v220, v186
	v_lshl_add_u64 v[208:209], v[208:209], 0, s[4:5]
	v_cvt_pk_bf16_f32 v213, v75, s0
	v_cvt_pk_bf16_f32 v214, v74, s0
	global_store_short v[208:209], v213, off
	global_store_short v[208:209], v214, off offset:128
	v_mul_f32_e32 v217, v70, v74
	v_mul_f32_e32 v218, v71, v74
	v_fma_f32 v219, v71, v75, v217
	v_fma_f32 v220, v70, v75, -v218
	s_waitcnt lgkmcnt(1)
	v_add_f32_e32 v74, v219, v189
	v_add_f32_e32 v75, v220, v188
	v_lshl_add_u64 v[208:209], v[208:209], 0, s[4:5]
	v_cvt_pk_bf16_f32 v215, v75, s0
	v_cvt_pk_bf16_f32 v216, v74, s0
	global_store_short v[208:209], v215, off
	global_store_short v[208:209], v216, off offset:128
	v_mul_f32_e32 v217, v70, v74
	v_mul_f32_e32 v218, v71, v74
	v_fma_f32 v219, v71, v75, v217
	v_fma_f32 v220, v70, v75, -v218
	s_waitcnt lgkmcnt(0)
	v_add_f32_e32 v74, v219, v191
	v_add_f32_e32 v75, v220, v190
	v_lshl_add_u64 v[208:209], v[208:209], 0, s[4:5]
	v_add_u32_e32 v212, 0x1000, v212
	s_add_i32 s25, s25, -1
	s_cmp_lg_u32 s25, 0
	s_cbranch_scc1 .Lsc_b0
	s_branch .Lsc_end
.Lsc_d1:
	v_add_u32_e32 v210, s90, v85
	v_add_u32_e32 v210, s92, v210
	v_mov_b32_e32 v211, 0
	v_lshlrev_b32_e32 v210, 15, v210
	v_lshl_add_u64 v[208:209], v[210:211], 0, v[66:67]
	s_add_i32 s4, s90, -7
	v_add_u32_e32 v212, s4, v85
	v_lshl_add_u32 v212, v212, 9, v84
	s_mov_b32 s4, 0xffff8000
	s_mov_b32 s5, -1
.Lsc_b1:
	s_waitcnt vmcnt(40)
	ds_read2st64_b32 v[190:191], v212 offset0:14 offset1:15
	ds_read2st64_b32 v[188:189], v212 offset0:12 offset1:13
	ds_read2st64_b32 v[186:187], v212 offset0:10 offset1:11
	ds_read2st64_b32 v[184:185], v212 offset0:8 offset1:9
	ds_read2st64_b32 v[182:183], v212 offset0:6 offset1:7
	ds_read2st64_b32 v[180:181], v212 offset0:4 offset1:5
	ds_read2st64_b32 v[178:179], v212 offset0:2 offset1:3
	ds_read2st64_b32 v[176:177], v212 offset0:0 offset1:1
	v_cvt_pk_bf16_f32 v213, v75, s0
	v_cvt_pk_bf16_f32 v214, v74, s0
	global_store_short v[208:209], v213, off
	global_store_short v[208:209], v214, off offset:128
	v_mul_f32_e32 v217, v70, v74
	v_mul_f32_e32 v218, v71, v74
	v_fma_f32 v219, v71, v75, v217
	v_fma_f32 v220, v70, v75, -v218
	s_waitcnt lgkmcnt(7)
	v_add_f32_e32 v74, v219, v191
	v_add_f32_e32 v75, v220, v190
	v_lshl_add_u64 v[208:209], v[208:209], 0, s[4:5]
	v_cvt_pk_bf16_f32 v215, v75, s0
	v_cvt_pk_bf16_f32 v216, v74, s0
	global_store_short v[208:209], v215, off
	global_store_short v[208:209], v216, off offset:128
	v_mul_f32_e32 v217, v70, v74
	v_mul_f32_e32 v218, v71, v74
	v_fma_f32 v219, v71, v75, v217
	v_fma_f32 v220, v70, v75, -v218
	s_waitcnt lgkmcnt(6)
	v_add_f32_e32 v74, v219, v189
	v_add_f32_e32 v75, v220, v188
	v_lshl_add_u64 v[208:209], v[208:209], 0, s[4:5]
	v_cvt_pk_bf16_f32 v213, v75, s0
	v_cvt_pk_bf16_f32 v214, v74, s0
	global_store_short v[208:209], v213, off
	global_store_short v[208:209], v214, off offset:128
	v_mul_f32_e32 v217, v70, v74
	v_mul_f32_e32 v218, v71, v74
	v_fma_f32 v219, v71, v75, v217
	v_fma_f32 v220, v70, v75, -v218
	s_waitcnt lgkmcnt(5)
	v_add_f32_e32 v74, v219, v187
	v_add_f32_e32 v75, v220, v186
	v_lshl_add_u64 v[208:209], v[208:209], 0, s[4:5]
	v_cvt_pk_bf16_f32 v215, v75, s0
	v_cvt_pk_bf16_f32 v216, v74, s0
	global_store_short v[208:209], v215, off
	global_store_short v[208:209], v216, off offset:128
	v_mul_f32_e32 v217, v70, v74
	v_mul_f32_e32 v218, v71, v74
	v_fma_f32 v219, v71, v75, v217
	v_fma_f32 v220, v70, v75, -v218
	s_waitcnt lgkmcnt(4)
	v_add_f32_e32 v74, v219, v185
	v_add_f32_e32 v75, v220, v184
	v_lshl_add_u64 v[208:209], v[208:209], 0, s[4:5]
	v_cvt_pk_bf16_f32 v213, v75, s0
	v_cvt_pk_bf16_f32 v214, v74, s0
	global_store_short v[208:209], v213, off
	global_store_short v[208:209], v214, off offset:128
	v_mul_f32_e32 v217, v70, v74
	v_mul_f32_e32 v218, v71, v74
	v_fma_f32 v219, v71, v75, v217
	v_fma_f32 v220, v70, v75, -v218
	s_waitcnt lgkmcnt(3)
	v_add_f32_e32 v74, v219, v183
	v_add_f32_e32 v75, v220, v182
	v_lshl_add_u64 v[208:209], v[208:209], 0, s[4:5]
	v_cvt_pk_bf16_f32 v215, v75, s0
	v_cvt_pk_bf16_f32 v216, v74, s0
	global_store_short v[208:209], v215, off
	global_store_short v[208:209], v216, off offset:128
	v_mul_f32_e32 v217, v70, v74
	v_mul_f32_e32 v218, v71, v74
	v_fma_f32 v219, v71, v75, v217
	v_fma_f32 v220, v70, v75, -v218
	s_waitcnt lgkmcnt(2)
	v_add_f32_e32 v74, v219, v181
	v_add_f32_e32 v75, v220, v180
	v_lshl_add_u64 v[208:209], v[208:209], 0, s[4:5]
	v_cvt_pk_bf16_f32 v213, v75, s0
	v_cvt_pk_bf16_f32 v214, v74, s0
	global_store_short v[208:209], v213, off
	global_store_short v[208:209], v214, off offset:128
	v_mul_f32_e32 v217, v70, v74
	v_mul_f32_e32 v218, v71, v74
	v_fma_f32 v219, v71, v75, v217
	v_fma_f32 v220, v70, v75, -v218
	s_waitcnt lgkmcnt(1)
	v_add_f32_e32 v74, v219, v179
	v_add_f32_e32 v75, v220, v178
	v_lshl_add_u64 v[208:209], v[208:209], 0, s[4:5]
	v_cvt_pk_bf16_f32 v215, v75, s0
	v_cvt_pk_bf16_f32 v216, v74, s0
	global_store_short v[208:209], v215, off
	global_store_short v[208:209], v216, off offset:128
	v_mul_f32_e32 v217, v70, v74
	v_mul_f32_e32 v218, v71, v74
	v_fma_f32 v219, v71, v75, v217
	v_fma_f32 v220, v70, v75, -v218
	s_waitcnt lgkmcnt(0)
	v_add_f32_e32 v74, v219, v177
	v_add_f32_e32 v75, v220, v176
	v_lshl_add_u64 v[208:209], v[208:209], 0, s[4:5]
	v_add_u32_e32 v212, 0xfffff000, v212
	s_add_i32 s25, s25, -1
	s_cmp_lg_u32 s25, 0
	s_cbranch_scc1 .Lsc_b1
.Lsc_end:
	s_and_b64 vcc, exec, s[30:31]
	s_cbranch_vccz .LBB0_695
	s_load_dwordx2 s[4:5], s[72:73], 0xe0
	s_waitcnt lgkmcnt(0)
	v_lshl_add_u64 v[70:71], v[72:73], 2, s[4:5]
	v_add_co_u32_e32 v72, vcc, 0x3000000, v70
	s_nop 1
	v_addc_co_u32_e32 v73, vcc, 0, v71, vcc
	v_add_co_u32_e32 v70, vcc, 0x3004000, v70
	global_store_dword v[72:73], v75, off
	s_nop 0
	v_addc_co_u32_e32 v71, vcc, 0, v71, vcc
	global_store_dword v[70:71], v74, off
	s_branch .LBB0_695
